# SSD prompt: wave 0 runs its serial prefix-sum/publish section at raised priority (s_setprio 3 .. 0)
# baseline (speedup 1.0000x reference)
.LBB0_846:
	s_and_saveexec_b64 s[78:79], s[4:5]
	s_cbranch_execz .LBB0_848
	s_setprio 3
	s_waitcnt vmcnt(1)
	v_mul_f32_e64 v42, v95, -v184
	s_nop 1
	v_add_f32_dpp v42, v42, v42 row_shr:1 row_mask:0xf bank_mask:0xf
	s_nop 1
	v_add_f32_dpp v42, v42, v42 row_shr:2 row_mask:0xf bank_mask:0xf
	s_nop 1
	v_add_f32_dpp v42, v42, v42 row_shr:4 row_mask:0xf bank_mask:0xf
	s_nop 1
	v_add_f32_dpp v42, v42, v42 row_shr:8 row_mask:0xf bank_mask:0xf
	s_nop 1
	v_add_f32_dpp v42, v42, v42 row_bcast:15 row_mask:0xa bank_mask:0xf
	s_nop 1
	v_add_f32_dpp v42, v42, v42 row_bcast:31 row_mask:0xc bank_mask:0xf
	ds_write_b32 v65, v42
	ds_write_b32 v85, v95
	v_readlane_b32 s99, v42, 63
	s_nop 1
	v_sub_f32_e32 v43, s99, v42
	v_mul_f32_e32 v43, 0x3fb8aa3b, v43
	v_exp_f32_e32 v43, v43
	s_nop 0
	v_mul_f32_e32 v43, v95, v43
	ds_write_b32 v65, v43 offset:512
	s_setprio 0
